# in-proj tile order: column groups re-dealt between even and odd workgroups (same weight half per XCD parity) so both get 3 rotary, 2 plain, 3 gate tiles
# baseline (speedup 1.0000x reference)
.LBB0_134:
	s_ashr_i32 s22, s38, 3
	s_add_i32 s22, s48, s22
	s_bfe_u32 s84, s22, 0x30005
	s_lshl_b32 s84, s84, 2
	s_mov_b32 s85, 0xdca94610
	s_bitcmp1_b32 s22, 8
	s_cselect_b32 s85, 0xfeb73258, s85
	s_lshr_b32 s85, s85, s84
	s_and_b32 s85, s85, 15
	s_lshl_b32 s85, s85, 5
	s_and_b32 s22, s22, 0xfffffe1f
	s_or_b32 s22, s22, s85
	s_ashr_i32 s23, s22, 31
	s_lshr_b32 s23, s23, 23
	s_add_i32 s23, s22, s23
	s_ashr_i32 s38, s23, 9
	s_lshl_b32 s38, s38, 3
	s_sub_i32 s39, 32, s38
	s_min_i32 s39, s39, 8
	s_abs_i32 s48, s39
	v_cvt_f32_u32_e32 v0, s48
	s_sub_i32 s50, 0, s48
	s_and_b32 s23, s23, 0xfffffe00
	s_sub_i32 s22, s22, s23
	v_rcp_iflag_f32_e32 v0, v0
	s_abs_i32 s23, s22
	s_xor_b32 s49, s22, s39
	s_ashr_i32 s49, s49, 31
	v_mul_f32_e32 v0, 0x4f7ffffe, v0
	v_cvt_u32_f32_e32 v0, v0
	s_nop 0
	v_readfirstlane_b32 s51, v0
	s_mul_i32 s50, s50, s51
	s_mul_hi_u32 s50, s51, s50
	s_add_i32 s51, s51, s50
	s_mul_hi_u32 s50, s23, s51
	s_mul_i32 s51, s50, s48
	s_sub_i32 s23, s23, s51
	s_add_i32 s52, s50, 1
	s_sub_i32 s51, s23, s48
	s_cmp_ge_u32 s23, s48
	s_cselect_b32 s50, s52, s50
	s_cselect_b32 s23, s51, s23
	s_add_i32 s51, s50, 1
	s_cmp_ge_u32 s23, s48
	s_cselect_b32 s23, s51, s50
	s_xor_b32 s23, s23, s49
	s_sub_i32 s48, s23, s49
	s_mul_i32 s23, s48, s39
	s_sub_i32 s22, s22, s23
	s_add_i32 s68, s38, s22
